# non-temporal (nt) loads on the once-read f32 weight and x streams (convert_weights, cast_rows)
# baseline (speedup 1.0000x reference)
; __device__ __forceinline__ void convert_weights(const KArgs& a, int l, LAS unsigned char* lds) {
;     ...
;         const int kt = r % nkt, rt = r / nkt, r0 = rt * 64, k0 = kt * 64;
;         __syncthreads();
;         if (mode == 1) {
; #pragma unroll
;             for (int e = 0; e < 8; ++e) { const int idx = tid + 512 * e, rl = idx & 63, kl = idx >> 6, rr = r0 + rl, k = k0 + kl;
;                 const int hh = rr / 192, ee = rr % 192; const int col = ee < 128 ? hh * 192 + ee : hh * 192 + 128 + ((ee - 128) & 1) * 32 + ((ee - 128) >> 1);
;                 tile[kl * 65 + rl] = w0[(size_t)k * N + col]; }
;         } else {
; #pragma unroll
;             for (int e = 0; e < 2; ++e) { const int idx = tid + 512 * e, r4 = (idx & 15) * 4, kl = idx >> 4, rr = r0 + r4, k = k0 + kl;
;                 f32x4 v = {0.f, 0.f, 0.f, 0.f};
;                 if (mode == 0) { if (rr < N) v = *(const f32x4*)(w0 + (size_t)k * N + rr); }
;                 else { const int g = rr >> 5, n = (rr >> 4) & 1, i = rr & 15; v = *(const f32x4*)((n ? w1 : w0) + (size_t)k * N + 16 * g + i); }
;                 if (gk) v = v * gk[k];
;                 tile[kl * 65 + r4] = v[0]; tile[kl * 65 + r4 + 1] = v[1]; tile[kl * 65 + r4 + 2] = v[2]; tile[kl * 65 + r4 + 3] = v[3]; }
.LBB0_42:
	v_cvt_f32_u32_e32 v1, s31
	s_sub_i32 s41, 0, s31
	s_abs_i32 s23, s30
	s_ashr_i32 s22, s30, 31
	v_rcp_iflag_f32_e32 v1, v1
	s_waitcnt lgkmcnt(0)
	s_barrier
	v_mul_f32_e32 v1, 0x4f7ffffe, v1
	v_cvt_u32_f32_e32 v1, v1
	s_nop 0
	v_readfirstlane_b32 s42, v1
	s_mul_i32 s41, s41, s42
	s_mul_hi_u32 s41, s42, s41
	s_add_i32 s42, s42, s41
	s_mul_hi_u32 s41, s23, s42
	s_mul_i32 s42, s41, s31
	s_sub_i32 s23, s23, s42
	s_add_i32 s43, s41, 1
	s_sub_i32 s42, s23, s31
	s_cmp_ge_u32 s23, s31
	s_cselect_b32 s41, s43, s41
	s_cselect_b32 s23, s42, s23
	s_add_i32 s42, s41, 1
	s_cmp_ge_u32 s23, s31
	s_cselect_b32 s23, s42, s41
	s_xor_b32 s23, s23, s22
	s_sub_i32 s22, s23, s22
	s_mul_i32 s31, s22, s31
	s_lshl_b32 s23, s22, 6
	s_sub_i32 s22, s30, s31
	s_lshl_b32 s22, s22, 6
	s_mov_b64 s[30:31], -1
	s_and_b64 vcc, exec, s[28:29]
	s_cbranch_vccnz .LBB0_52
	v_mov_b32_e32 v1, s27
	v_mov_b32_e32 v3, s17
	v_or_b32_e32 v2, s23, v14
	v_cndmask_b32_e64 v5, v1, v3, s[4:5]
	v_mov_b32_e32 v1, s26
	v_mov_b32_e32 v3, s16
	v_cndmask_b32_e64 v4, v1, v3, s[4:5]
	v_ashrrev_i32_e32 v1, 1, v2
	v_and_b32_e32 v10, -16, v1
	v_ashrrev_i32_e32 v11, 31, v10
	v_lshl_add_u64 v[4:5], v[10:11], 2, v[4:5]
	v_mov_b32_e32 v7, v0
	v_ashrrev_i32_e32 v3, 31, v2
	v_lshl_add_u64 v[4:5], v[4:5], 0, v[6:7]
	v_cmp_gt_i32_e32 vcc, s40, v2
	v_lshl_add_u64 v[10:11], v[2:3], 2, s[16:17]
	v_mov_b32_e32 v2, v0
	v_mov_b32_e32 v3, v0
	v_add_u32_e32 v12, s22, v18
	v_mov_b32_e32 v1, v0
	v_cndmask_b32_e64 v11, v11, v5, s[24:25]
	v_cndmask_b32_e64 v10, v10, v4, s[24:25]
	v_mov_b64_e32 v[4:5], v[2:3]
	s_or_b64 s[26:27], s[24:25], vcc
	v_ashrrev_i32_e32 v13, 31, v12
	v_mov_b64_e32 v[2:3], v[0:1]
	v_mov_b32_e32 v62, v0
	v_mov_b32_e32 v63, v0
	v_mov_b32_e32 v64, v0
	v_mov_b32_e32 v65, v0
	v_add_u32_e32 v66, s22, v19
	v_ashrrev_i32_e32 v67, 31, v66
	s_and_saveexec_b64 s[24:25], s[26:27]
	s_cbranch_execz .LBB0_45
	v_mad_u64_u32 v[2:3], s[28:29], v12, s40, 0
	v_mov_b32_e32 v4, v3
	v_mad_u64_u32 v[4:5], s[28:29], v13, s40, v[4:5]
	v_mov_b32_e32 v3, v4
	v_lshl_add_u64 v[2:3], v[2:3], 2, v[10:11]
	v_mad_u64_u32 v[62:63], s[28:29], v66, s40, 0
	v_mov_b32_e32 v64, v63
	v_mad_u64_u32 v[64:65], s[28:29], v67, s40, v[64:65]
	v_mov_b32_e32 v63, v64
	v_lshl_add_u64 v[62:63], v[62:63], 2, v[10:11]
	global_load_dwordx4 v[2:5], v[2:3], off nt
	global_load_dwordx4 v[62:65], v[62:63], off nt

; __device__ __forceinline__ void cast_rows_bf16(const float* src, bf16_t* dst, float* rsq) {
;     ...
;     for (int m = gw; m < M; m += ngw) {
;         const f32x4* xr = (const f32x4*)(src + (size_t)m * DM) + lane;
;         f32x4 v[8]; float s = 0.f;
; #pragma unroll
;         for (int j = 0; j < 8; ++j) { v[j] = xr[64 * j]; s += (v[j][0] * v[j][0] + v[j][1] * v[j][1]) + (v[j][2] * v[j][2] + v[j][3] * v[j][3]); }
;         s = wave_sum(s);
;         if (lane == 0) rsq[m] = s;
.LBB0_59:
	global_load_dwordx4 v[0:3], v[36:37], off offset:-4096 nt
	global_load_dwordx4 v[4:7], v[36:37], off offset:-3072 nt
	global_load_dwordx4 v[8:11], v[36:37], off offset:-2048 nt
	global_load_dwordx4 v[12:15], v[36:37], off offset:-1024 nt
	global_load_dwordx4 v[16:19], v[36:37], off nt
	global_load_dwordx4 v[20:23], v[36:37], off offset:1024 nt
	global_load_dwordx4 v[24:27], v[36:37], off offset:2048 nt
	global_load_dwordx4 v[28:31], v[36:37], off offset:3072 nt
	s_waitcnt vmcnt(0)
	v_mul_f32_e32 v33, v1, v1
	s_waitcnt lgkmcnt(0)
	v_mul_f32_e32 v47, v3, v3
	v_mul_f32_e32 v48, v5, v5
	v_mul_f32_e32 v49, v7, v7
	v_mul_f32_e32 v50, v9, v9
	v_mul_f32_e32 v51, v11, v11
	v_fmac_f32_e32 v33, v0, v0
	v_fmac_f32_e32 v47, v2, v2
	v_fmac_f32_e32 v48, v4, v4
	v_fmac_f32_e32 v49, v6, v6
	v_mul_f32_e32 v52, v13, v13
	v_mul_f32_e32 v53, v15, v15
	v_fmac_f32_e32 v50, v8, v8
	v_fmac_f32_e32 v51, v10, v10
	v_add_f32_e32 v33, v33, v47
	v_add_f32_e32 v47, v48, v49
	v_mul_f32_e32 v54, v17, v17
	v_mul_f32_e32 v55, v19, v19
	v_fmac_f32_e32 v52, v12, v12
	v_fmac_f32_e32 v53, v14, v14
	v_add_f32_e32 v48, v50, v51
	v_add_f32_e32 v33, v33, v47
	v_mul_f32_e32 v56, v21, v21
	v_mul_f32_e32 v57, v23, v23
	v_fmac_f32_e32 v54, v16, v16
	v_fmac_f32_e32 v55, v18, v18
	v_add_f32_e32 v49, v52, v53
	v_add_f32_e32 v33, v33, v48
	v_mul_f32_e32 v58, v25, v25
	v_mul_f32_e32 v59, v27, v27
	v_fmac_f32_e32 v56, v20, v20
	v_fmac_f32_e32 v57, v22, v22
	v_add_f32_e32 v50, v54, v55
	v_add_f32_e32 v33, v33, v49
	v_mul_f32_e32 v60, v29, v29
	v_mul_f32_e32 v61, v31, v31
	v_fmac_f32_e32 v58, v24, v24
	v_fmac_f32_e32 v59, v26, v26
	v_add_f32_e32 v51, v56, v57
	v_add_f32_e32 v33, v33, v50
	v_fmac_f32_e32 v60, v28, v28
	v_fmac_f32_e32 v61, v30, v30
	v_add_f32_e32 v52, v58, v59
	v_add_f32_e32 v33, v33, v51
	v_add_f32_e32 v33, v33, v52
	v_add_f32_e32 v47, v60, v61
	v_add_f32_e32 v33, v33, v47
	ds_bpermute_b32 v47, v41, v33
	s_waitcnt lgkmcnt(0)
	v_add_f32_e32 v33, v33, v47
	ds_bpermute_b32 v47, v42, v33
	s_waitcnt lgkmcnt(0)
	v_add_f32_e32 v33, v33, v47
	ds_bpermute_b32 v47, v43, v33
	s_waitcnt lgkmcnt(0)
	v_add_f32_e32 v33, v33, v47
	ds_bpermute_b32 v47, v44, v33
	s_waitcnt lgkmcnt(0)
	v_add_f32_e32 v33, v33, v47
	ds_bpermute_b32 v47, v45, v33
	s_waitcnt lgkmcnt(0)
	v_add_f32_e32 v33, v33, v47
	ds_bpermute_b32 v47, v46, v33
	s_and_saveexec_b64 s[4:5], vcc
	s_cbranch_execz .LBB0_58
	s_waitcnt lgkmcnt(0)
	v_add_f32_e32 v33, v33, v47
	global_store_dword v[34:35], v33, off
	s_branch .LBB0_58

; __device__ __forceinline__ void convert_weights(const KArgs& a, int l, LAS unsigned char* lds) {
;     ...
;         const int kt = r % nkt, rt = r / nkt, r0 = rt * 64, k0 = kt * 64;
;         __syncthreads();
;         if (mode == 1) {
; #pragma unroll
;             for (int e = 0; e < 8; ++e) { const int idx = tid + 512 * e, rl = idx & 63, kl = idx >> 6, rr = r0 + rl, k = k0 + kl;
;                 const int hh = rr / 192, ee = rr % 192; const int col = ee < 128 ? hh * 192 + ee : hh * 192 + 128 + ((ee - 128) & 1) * 32 + ((ee - 128) >> 1);
;                 tile[kl * 65 + rl] = w0[(size_t)k * N + col]; }
;         } else {
; #pragma unroll
;             for (int e = 0; e < 2; ++e) { const int idx = tid + 512 * e, r4 = (idx & 15) * 4, kl = idx >> 4, rr = r0 + r4, k = k0 + kl;
;                 f32x4 v = {0.f, 0.f, 0.f, 0.f};
;                 if (mode == 0) { if (rr < N) v = *(const f32x4*)(w0 + (size_t)k * N + rr); }
;                 else { const int g = rr >> 5, n = (rr >> 4) & 1, i = rr & 15; v = *(const f32x4*)((n ? w1 : w0) + (size_t)k * N + 16 * g + i); }
;                 if (gk) v = v * gk[k];
;                 tile[kl * 65 + r4] = v[0]; tile[kl * 65 + r4 + 1] = v[1]; tile[kl * 65 + r4 + 2] = v[2]; tile[kl * 65 + r4 + 3] = v[3]; }
.LBB0_129:
	v_cvt_f32_u32_e32 v0, s37
	s_sub_i32 s40, 0, s37
	s_abs_i32 s29, s36
	s_ashr_i32 s28, s36, 31
	v_rcp_iflag_f32_e32 v0, v0
	s_movk_i32 s2, 0x2a00
	s_barrier
	v_mul_f32_e32 v0, 0x4f7ffffe, v0
	v_cvt_u32_f32_e32 v0, v0
	s_nop 0
	v_readfirstlane_b32 s41, v0
	s_mul_i32 s40, s40, s41
	s_mul_hi_u32 s40, s41, s40
	s_add_i32 s41, s41, s40
	s_mul_hi_u32 s40, s29, s41
	s_mul_i32 s41, s40, s37
	s_sub_i32 s29, s29, s41
	s_add_i32 s42, s40, 1
	s_sub_i32 s41, s29, s37
	s_cmp_ge_u32 s29, s37
	s_cselect_b32 s40, s42, s40
	s_cselect_b32 s29, s41, s29
	s_add_i32 s41, s40, 1
	s_cmp_ge_u32 s29, s37
	s_cselect_b32 s29, s41, s40
	s_xor_b32 s29, s29, s28
	s_sub_i32 s28, s29, s28
	s_mul_i32 s37, s28, s37
	s_lshl_b32 s29, s28, 6
	s_sub_i32 s28, s36, s37
	s_lshl_b32 s28, s28, 6
	s_mov_b64 s[36:37], -1
	s_and_b64 vcc, exec, s[34:35]
	s_cbranch_vccnz .LBB0_139
	v_mov_b32_e32 v1, s31
	v_mov_b32_e32 v2, s23
	v_or_b32_e32 v0, s29, v12
	v_cndmask_b32_e64 v3, v1, v2, s[4:5]
	v_mov_b32_e32 v1, s30
	v_mov_b32_e32 v2, s22
	v_cndmask_b32_e64 v2, v1, v2, s[4:5]
	v_ashrrev_i32_e32 v1, 1, v0
	v_and_b32_e32 v8, -16, v1
	v_ashrrev_i32_e32 v9, 31, v8
	v_lshl_add_u64 v[2:3], v[8:9], 2, v[2:3]
	v_mov_b32_e32 v5, v113
	v_ashrrev_i32_e32 v1, 31, v0
	v_lshl_add_u64 v[2:3], v[2:3], 0, v[4:5]
	v_cmp_gt_i32_e32 vcc, s39, v0
	v_lshl_add_u64 v[0:1], v[0:1], 2, s[22:23]
	v_mov_b32_e32 v112, v113
	v_add_u32_e32 v10, s28, v16
	v_mov_b32_e32 v114, v113
	v_mov_b32_e32 v115, v113
	v_cndmask_b32_e64 v9, v1, v3, s[26:27]
	v_cndmask_b32_e64 v8, v0, v2, s[26:27]
	v_mov_b64_e32 v[0:1], v[112:113]
	s_or_b64 s[30:31], s[26:27], vcc
	v_ashrrev_i32_e32 v11, 31, v10
	v_mov_b64_e32 v[2:3], v[114:115]
	v_mov_b32_e32 v62, v113
	v_mov_b32_e32 v63, v113
	v_mov_b32_e32 v64, v113
	v_mov_b32_e32 v65, v113
	v_add_u32_e32 v66, s28, v17
	v_ashrrev_i32_e32 v67, 31, v66
	s_and_saveexec_b64 s[26:27], s[30:31]
	s_cbranch_execz .LBB0_132
	v_mad_u64_u32 v[0:1], s[34:35], v10, s39, 0
	v_mov_b32_e32 v2, v1
	v_mad_u64_u32 v[2:3], s[34:35], v11, s39, v[2:3]
	v_mov_b32_e32 v1, v2
	v_lshl_add_u64 v[0:1], v[0:1], 2, v[8:9]
	v_mad_u64_u32 v[62:63], s[34:35], v66, s39, 0
	v_mov_b32_e32 v64, v63
	v_mad_u64_u32 v[64:65], s[34:35], v67, s39, v[64:65]
	v_mov_b32_e32 v63, v64
	v_lshl_add_u64 v[62:63], v[62:63], 2, v[8:9]
	global_load_dwordx4 v[0:3], v[0:1], off nt
	global_load_dwordx4 v[62:65], v[62:63], off nt
